# moba items: static two-item pairing per workgroup chosen for three measured workgroup classes (scan+prep: jb 0/1 then 12/11; prep only: 9/8 then 5/6; no prep but slower on their CU: 15/14/13/10 then 2
# speedup vs baseline: 1.0218x; 1.0218x over previous
.Lb3_arr_done:
.LBB0_481:
	s_or_b64 exec, exec, s[4:5]
	s_mov_b32 s98, 0
	s_nop 0
	v_writelane_b32 v255, s98, 14
	v_writelane_b32 v255, s98, 19
	s_branch .LBB0_486

.LBB0_565:
	s_cbranch_execz .LBB0_643
	s_lshl_b32 s0, s76, 2
	s_and_b32 s73, s0, 28
	s_lshl_b32 s0, s76, 11
	s_ashr_i32 s33, s76, 3
	s_lshr_b32 s98, s33, 3
	s_lshl_b32 s98, s98, 2
	s_lshr_b32 s98, 0xadef8910, s98
	s_and_b32 s98, s98, 15
	s_sub_i32 s98, 15, s98
	s_lshl_b32 s98, s98, 3
	s_and_b32 s33, s33, 7
	s_or_b32 s33, s33, s98
	s_and_b32 s52, s0, 0x3000
	s_ashr_i32 s2, s42, 3
	s_not_b32 s72, s33
	s_or_b32 s74, s52, 64
	s_add_u32 s66, s58, 0x2cd1000
	s_addc_u32 s67, s59, 0
	s_add_u32 s75, s58, 0x8cd1000
	s_addc_u32 s77, s59, 0
	s_add_u32 s78, s58, 0xbd0000
	v_mbcnt_lo_u32_b32 v0, -1, 0
	s_addc_u32 s79, s59, 0
	v_mbcnt_hi_u32_b32 v196, -1, v0
	s_mov_b32 s63, 0
	s_add_u32 s68, s58, 0xcd1000
	v_and_b32_e32 v0, 64, v196
	s_mov_b32 s53, s63
	s_addc_u32 s69, s59, 0
	v_mov_b32_e32 v33, 0
	s_movk_i32 s80, 0xff
	s_movk_i32 s81, 0x1800
	s_mov_b32 s82, 0xefa18f08
	v_xor_b32_e32 v197, 32, v196
	v_add_u32_e32 v198, 64, v0
	v_mov_b32_e32 v199, 0xff800000
	v_mov_b32_e32 v200, 0x3f803f80
	s_mov_b32 s6, 0
	s_mov_b32 s83, 0
	v_readlane_b32 s98, v255, 14
	s_nop 3
	s_cmp_lg_u32 s98, 0
	s_cbranch_scc1 .Lmoba_dq_latch2
	s_branch .LBB0_569

.Lmoba_dq_latch2:
	s_waitcnt lgkmcnt(0)
	s_barrier
	v_readlane_b32 s98, v255, 19
	s_nop 3
	s_cmp_lg_u32 s98, 0
	s_cbranch_scc1 .LBB0_643
	s_mov_b32 s98, 1
	s_nop 0
	v_writelane_b32 v255, s98, 19
	s_ashr_i32 s14, s76, 3
	s_lshr_b32 s0, s14, 3
	s_lshl_b32 s0, s0, 2
	s_lshr_b32 s0, 0x743265bc, s0
	s_and_b32 s0, s0, 15
	s_sub_i32 s0, 15, s0
	s_lshl_b32 s0, s0, 3
	s_and_b32 s14, s14, 7
	s_or_b32 s14, s14, s0
	s_branch .LBB0_574
